# v21 plus mad_u32_u24 merges and the x4 shift folded into v_lshl_add_u64 in the sample attention loop (load and fused-copy store address paths)
# baseline (speedup 1.0000x reference)
.LBB0_1288:
	s_and_b64 exec, exec, s[16:17]
	v_add_u32_e32 v120, v156, v200
	v_lshl_add_u64 v[44:45], v[120:121], 2, v[144:145]
	v_lshl_add_u64 v[42:43], v[120:121], 2, v[146:147]
	global_store_dwordx4 v[44:45], v[112:115], off nt
	global_store_dwordx4 v[42:43], v[116:119], off nt

.LBB0_1293:
	s_and_b64 exec, exec, s[16:17]
	v_add_u32_e32 v120, v156, v184
	v_lshl_add_u64 v[44:45], v[120:121], 2, v[144:145]
	v_lshl_add_u64 v[42:43], v[120:121], 2, v[146:147]
	global_store_dwordx4 v[44:45], v[104:107], off nt
	global_store_dwordx4 v[42:43], v[108:111], off nt

.LBB0_1298:
	s_and_b64 exec, exec, s[16:17]
	v_add_u32_e32 v120, v156, v188
	v_lshl_add_u64 v[44:45], v[120:121], 2, v[144:145]
	v_lshl_add_u64 v[42:43], v[120:121], 2, v[146:147]
	global_store_dwordx4 v[44:45], v[96:99], off nt
	global_store_dwordx4 v[42:43], v[100:103], off nt

.LBB0_1303:
	s_and_b64 exec, exec, s[16:17]
	v_add_u32_e32 v120, v156, v190
	v_lshl_add_u64 v[44:45], v[120:121], 2, v[144:145]
	v_lshl_add_u64 v[42:43], v[120:121], 2, v[146:147]
	global_store_dwordx4 v[44:45], v[88:91], off nt
	global_store_dwordx4 v[42:43], v[92:95], off nt

.LBB0_1308:
	s_and_b64 exec, exec, s[16:17]
	v_add_u32_e32 v120, v156, v192
	v_lshl_add_u64 v[44:45], v[120:121], 2, v[144:145]
	v_lshl_add_u64 v[42:43], v[120:121], 2, v[146:147]
	global_store_dwordx4 v[44:45], v[80:83], off nt
	global_store_dwordx4 v[42:43], v[84:87], off nt

.LBB0_1313:
	s_and_b64 exec, exec, s[16:17]
	v_add_u32_e32 v120, v156, v194
	v_lshl_add_u64 v[44:45], v[120:121], 2, v[144:145]
	v_lshl_add_u64 v[42:43], v[120:121], 2, v[146:147]
	global_store_dwordx4 v[44:45], v[64:67], off nt
	global_store_dwordx4 v[42:43], v[68:71], off nt

.LBB0_1318:
	s_and_b64 exec, exec, s[16:17]
	v_add_u32_e32 v120, v156, v196
	v_lshl_add_u64 v[44:45], v[120:121], 2, v[144:145]
	v_lshl_add_u64 v[42:43], v[120:121], 2, v[146:147]
	global_store_dwordx4 v[44:45], v[72:75], off nt
	global_store_dwordx4 v[42:43], v[76:79], off nt

.LBB0_1323:
	s_and_b64 exec, exec, s[16:17]
	v_add_u32_e32 v120, v156, v198
	v_lshl_add_u64 v[42:43], v[120:121], 2, v[144:145]
	global_store_dwordx4 v[42:43], v[32:35], off nt
	s_nop 1
	v_lshl_add_u64 v[32:33], v[120:121], 2, v[146:147]
	global_store_dwordx4 v[32:33], v[36:39], off nt

.LBB0_1326:
	v_subrev_u32_e32 v32, 28, v182
	v_min_i32_e32 v32, s53, v32
	v_mad_u32_u24 v32, v32, v177, v178
	v_add_u32_e32 v33, -8, v32
	v_cmp_lt_i32_e32 vcc, v32, v180
	v_add_u32_e32 v211, v127, v129
	ds_read_b128 v[216:219], v211 offset:64
	v_cndmask_b32_e32 v32, v33, v32, vcc
	v_mad_u32_u24 v32, v32, v141, v130
	v_mov_b32_e32 v33, 0
	v_cndmask_b32_e32 v35, v145, v149, vcc
	v_cndmask_b32_e32 v34, v144, v148, vcc
	v_lshl_add_u64 v[34:35], v[32:33], 2, v[34:35]
	global_load_dwordx4 v[112:115], v[34:35], off
	v_cndmask_b32_e32 v35, v147, v151, vcc
	v_cndmask_b32_e32 v34, v146, v150, vcc
	v_lshl_add_u64 v[32:33], v[32:33], 2, v[34:35]
	global_load_dwordx4 v[116:119], v[32:33], off
	v_subrev_u32_e32 v32, 24, v182
	v_min_i32_e32 v32, s53, v32
	v_mad_u32_u24 v32, v32, v177, v178
	v_add_u32_e32 v33, -8, v32
	v_cmp_lt_i32_e32 vcc, v32, v180
	v_min_i32_e32 v120, s53, v182
	v_mul_u32_u24_e32 v120, v120, v177
	v_cndmask_b32_e32 v32, v33, v32, vcc
	v_mad_u32_u24 v32, v32, v141, v130
	v_mov_b32_e32 v33, 0
	v_cndmask_b32_e32 v35, v145, v149, vcc
	v_cndmask_b32_e32 v34, v144, v148, vcc
	v_lshl_add_u64 v[34:35], v[32:33], 2, v[34:35]
	global_load_dwordx4 v[104:107], v[34:35], off
	v_cndmask_b32_e32 v35, v147, v151, vcc
	v_cndmask_b32_e32 v34, v146, v150, vcc
	v_lshl_add_u64 v[32:33], v[32:33], 2, v[34:35]
	global_load_dwordx4 v[108:111], v[32:33], off
	v_subrev_u32_e32 v32, 20, v182
	v_min_i32_e32 v32, s53, v32
	v_mad_u32_u24 v32, v32, v177, v178
	v_add_u32_e32 v33, -8, v32
	v_cmp_lt_i32_e32 vcc, v32, v180
	v_add_u32_e32 v120, v120, v178
	v_add_u32_e32 v209, -8, v120
	v_cndmask_b32_e32 v32, v33, v32, vcc
	v_mad_u32_u24 v32, v32, v141, v130
	v_mov_b32_e32 v33, 0
	v_cndmask_b32_e32 v35, v145, v149, vcc
	v_cndmask_b32_e32 v34, v144, v148, vcc
	v_lshl_add_u64 v[34:35], v[32:33], 2, v[34:35]
	global_load_dwordx4 v[96:99], v[34:35], off
	v_cndmask_b32_e32 v35, v147, v151, vcc
	v_cndmask_b32_e32 v34, v146, v150, vcc
	v_lshl_add_u64 v[32:33], v[32:33], 2, v[34:35]
	global_load_dwordx4 v[100:103], v[32:33], off
	v_add_u32_e32 v32, -16, v182
	v_min_i32_e32 v32, s53, v32
	v_mad_u32_u24 v32, v32, v177, v178
	v_add_u32_e32 v33, -8, v32
	v_cmp_lt_i32_e32 vcc, v32, v180
	v_add_u32_e32 v184, v184, v186
	v_add_u32_e32 v201, v201, v185
	v_cndmask_b32_e32 v32, v33, v32, vcc
	v_mad_u32_u24 v32, v32, v141, v130
	v_mov_b32_e32 v33, 0
	v_cndmask_b32_e32 v35, v145, v149, vcc
	v_cndmask_b32_e32 v34, v144, v148, vcc
	v_lshl_add_u64 v[34:35], v[32:33], 2, v[34:35]
	global_load_dwordx4 v[88:91], v[34:35], off
	v_cndmask_b32_e32 v35, v147, v151, vcc
	v_cndmask_b32_e32 v34, v146, v150, vcc
	v_lshl_add_u64 v[32:33], v[32:33], 2, v[34:35]
	global_load_dwordx4 v[92:95], v[32:33], off
	v_add_u32_e32 v32, -12, v182
	v_min_i32_e32 v32, s53, v32
	v_mad_u32_u24 v32, v32, v177, v178
	v_add_u32_e32 v33, -8, v32
	v_cmp_lt_i32_e32 vcc, v32, v180
	ds_read_b128 v[212:215], v211 offset:32
	v_add_u32_e32 v188, v188, v186
	v_cndmask_b32_e32 v32, v33, v32, vcc
	v_mad_u32_u24 v32, v32, v141, v130
	v_mov_b32_e32 v33, 0
	v_cndmask_b32_e32 v35, v145, v149, vcc
	v_cndmask_b32_e32 v34, v144, v148, vcc
	v_lshl_add_u64 v[34:35], v[32:33], 2, v[34:35]
	global_load_dwordx4 v[80:83], v[34:35], off
	v_cndmask_b32_e32 v35, v147, v151, vcc
	v_cndmask_b32_e32 v34, v146, v150, vcc
	v_lshl_add_u64 v[32:33], v[32:33], 2, v[34:35]
	global_load_dwordx4 v[84:87], v[32:33], off
	v_add_u32_e32 v32, -8, v182
	v_min_i32_e32 v32, s53, v32
	v_mad_u32_u24 v32, v32, v177, v178
	v_add_u32_e32 v33, -8, v32
	v_cmp_lt_i32_e32 vcc, v32, v180
	v_add_u32_e32 v190, v190, v186
	v_add_u32_e32 v192, v192, v186
	v_cndmask_b32_e32 v32, v33, v32, vcc
	v_mad_u32_u24 v32, v32, v141, v130
	v_mov_b32_e32 v33, 0
	v_cndmask_b32_e32 v35, v145, v149, vcc
	v_cndmask_b32_e32 v34, v144, v148, vcc
	v_lshl_add_u64 v[34:35], v[32:33], 2, v[34:35]
	global_load_dwordx4 v[64:67], v[34:35], off
	v_cndmask_b32_e32 v35, v147, v151, vcc
	v_cndmask_b32_e32 v34, v146, v150, vcc
	v_lshl_add_u64 v[32:33], v[32:33], 2, v[34:35]
	global_load_dwordx4 v[68:71], v[32:33], off
	v_add_u32_e32 v32, -4, v182
	v_min_i32_e32 v32, s53, v32
	v_mul_u32_u24_e32 v32, v32, v177
	v_add_u32_e32 v32, v32, v178
	v_add_u32_e32 v33, -8, v32
	v_cmp_lt_i32_e32 vcc, v32, v180
	v_add_u32_e32 v182, 32, v182
	v_add_u32_e32 v194, v194, v186
	v_cndmask_b32_e32 v32, v33, v32, vcc
	v_mul_u32_u24_e32 v32, v32, v141
	v_or_b32_e32 v36, v32, v130
	v_mov_b32_e32 v37, 0
	ds_read_b128 v[32:35], v211
	v_cndmask_b32_e32 v39, v145, v149, vcc
	v_cndmask_b32_e32 v38, v144, v148, vcc
	v_lshlrev_b64 v[76:77], 2, v[36:37]
	v_lshl_add_u64 v[36:37], v[38:39], 0, v[76:77]
	global_load_dwordx4 v[72:75], v[36:37], off
	s_waitcnt lgkmcnt(0)
	v_mfma_f32_32x32x16_bf16 v[32:47], v[32:35], v[56:59], 0
	v_cndmask_b32_e32 v79, v147, v151, vcc
	v_cndmask_b32_e32 v78, v146, v150, vcc
	v_cmp_lt_i32_e32 vcc, v120, v180
	v_lshl_add_u64 v[76:77], v[78:79], 0, v[76:77]
	global_load_dwordx4 v[76:79], v[76:77], off
	v_cndmask_b32_e32 v120, v209, v120, vcc
	v_mul_u32_u24_e32 v220, v120, v141
	v_mfma_f32_32x32x16_bf16 v[32:47], v[212:215], v[60:63], v[32:47]
	ds_read_b128 v[212:215], v211 offset:96
	v_add_u32_e32 v196, v196, v186
	v_add_u32_e32 v198, v198, v186
	v_add_u32_e32 v200, v200, v186
	v_mfma_f32_32x32x16_bf16 v[32:47], v[216:219], v[52:55], v[32:47]
	v_add_u32_e32 v120, s33, v181
	v_cmp_le_u32_e64 s[16:17], v120, v135
	v_or_b32_e32 v218, v220, v130
	v_mov_b32_e32 v219, 0
	v_cndmask_b32_e32 v217, v145, v149, vcc
	s_waitcnt lgkmcnt(0)
	v_mfma_f32_32x32x16_bf16 v[32:47], v[212:215], v[48:51], v[32:47]
	v_cndmask_b32_e32 v216, v144, v148, vcc
	v_lshlrev_b64 v[218:219], 2, v[218:219]
	s_sub_i32 s33, s33, 32
	s_nop 8
	v_cndmask_b32_e64 v210, v173, v32, s[16:17]
	v_add_u32_e32 v32, -1, v120
	v_cmp_le_u32_e64 s[16:17], v32, v135
	s_nop 1
	v_cndmask_b32_e64 v212, v173, v33, s[16:17]
	v_add_u32_e32 v33, -2, v120
	v_cmp_le_u32_e64 s[16:17], v33, v135
	v_add_u32_e32 v33, -3, v120
	v_max3_f32 v32, v210, s90, v212
	v_cndmask_b32_e64 v213, v173, v34, s[16:17]
	v_cmp_le_u32_e64 s[16:17], v33, v135
	v_add_u32_e32 v33, -8, v120
	s_nop 0
	v_cndmask_b32_e64 v214, v173, v35, s[16:17]
	v_cmp_le_u32_e64 s[16:17], v33, v135
	v_add_u32_e32 v33, -9, v120
	v_max3_f32 v32, v32, v213, v214
	v_cndmask_b32_e64 v215, v173, v36, s[16:17]
	v_cmp_le_u32_e64 s[16:17], v33, v135
	v_add_u32_e32 v33, -10, v120
	v_cndmask_b32_e32 v36, v146, v150, vcc
	v_cndmask_b32_e64 v220, v173, v37, s[16:17]
	v_cmp_le_u32_e64 s[16:17], v33, v135
	v_add_u32_e32 v33, -11, v120
	v_max3_f32 v32, v32, v215, v220
	v_cndmask_b32_e64 v221, v173, v38, s[16:17]
	v_cmp_le_u32_e64 s[16:17], v33, v135
	v_add_u32_e32 v33, -16, v120
	v_cndmask_b32_e32 v37, v147, v151, vcc
	v_cndmask_b32_e64 v222, v173, v39, s[16:17]
	v_cmp_le_u32_e64 s[16:17], v33, v135
	v_subrev_u32_e32 v33, 17, v120
	v_max3_f32 v32, v32, v221, v222
	v_cndmask_b32_e64 v40, v173, v40, s[16:17]
	v_cmp_le_u32_e64 s[16:17], v33, v135
	v_subrev_u32_e32 v33, 18, v120
	v_lshl_add_u64 v[36:37], v[36:37], 0, v[218:219]
	v_cndmask_b32_e64 v41, v173, v41, s[16:17]
	v_cmp_le_u32_e64 s[16:17], v33, v135
	v_subrev_u32_e32 v33, 19, v120
	v_max3_f32 v32, v32, v40, v41
	v_cndmask_b32_e64 v42, v173, v42, s[16:17]
	v_cmp_le_u32_e64 s[16:17], v33, v135
	v_subrev_u32_e32 v33, 24, v120
	s_nop 0
	v_cndmask_b32_e64 v43, v173, v43, s[16:17]
	v_cmp_le_u32_e64 s[16:17], v33, v135
	v_subrev_u32_e32 v33, 25, v120
	v_max3_f32 v32, v32, v42, v43
	v_cndmask_b32_e64 v44, v173, v44, s[16:17]
	v_cmp_le_u32_e64 s[16:17], v33, v135
	v_subrev_u32_e32 v33, 26, v120
	s_nop 0
	v_cndmask_b32_e64 v45, v173, v45, s[16:17]
	v_cmp_le_u32_e64 s[16:17], v33, v135
	v_subrev_u32_e32 v33, 27, v120
	v_max3_f32 v32, v32, v44, v45
	v_cndmask_b32_e64 v46, v173, v46, s[16:17]
	v_cmp_le_u32_e64 s[16:17], v33, v135
	s_nop 1
	v_cndmask_b32_e64 v47, v173, v47, s[16:17]
	v_max3_f32 v38, v32, v46, v47
	ds_bpermute_b32 v39, v143, v38
	v_lshl_add_u64 v[32:33], v[216:217], 0, v[218:219]
	global_load_dwordx4 v[32:35], v[32:33], off
	s_add_i32 s16, s18, s33
	s_cmp_lg_u32 s16, 0
	s_waitcnt lgkmcnt(0)
	v_max3_f32 v209, v208, v38, v39
	v_sub_f32_e32 v38, v210, v209
	v_exp_f32_e32 v210, v38
	global_load_dwordx4 v[36:39], v[36:37], off
	v_sub_f32_e32 v212, v212, v209
	v_exp_f32_e32 v212, v212
	v_sub_f32_e32 v213, v213, v209
	v_exp_f32_e32 v213, v213
	v_sub_f32_e32 v214, v214, v209
	v_exp_f32_e32 v214, v214
	v_sub_f32_e32 v215, v215, v209
	v_sub_f32_e32 v120, v208, v209
	v_add_f32_e32 v208, 0, v210
	v_exp_f32_e32 v215, v215
	v_sub_f32_e32 v216, v220, v209
	v_add_f32_e32 v208, v212, v208
	v_exp_f32_e32 v216, v216
	v_sub_f32_e32 v217, v221, v209
	v_add_f32_e32 v208, v213, v208
	v_exp_f32_e32 v217, v217
	v_sub_f32_e32 v218, v222, v209
	v_add_f32_e32 v208, v214, v208
	v_exp_f32_e32 v218, v218
	v_sub_f32_e32 v40, v40, v209
	v_add_f32_e32 v208, v215, v208
	v_exp_f32_e32 v220, v40
	v_sub_f32_e32 v41, v41, v209
	v_add_f32_e32 v40, v216, v208
	v_exp_f32_e32 v208, v41
	v_sub_f32_e32 v41, v42, v209
	v_add_f32_e32 v40, v217, v40
	v_exp_f32_e32 v221, v41
	v_sub_f32_e32 v41, v43, v209
	v_add_f32_e32 v40, v218, v40
	v_exp_f32_e32 v222, v41
	v_sub_f32_e32 v41, v44, v209
	v_add_f32_e32 v40, v220, v40
	v_exp_f32_e32 v223, v41
	v_sub_f32_e32 v41, v45, v209
	v_add_f32_e32 v40, v208, v40
	v_exp_f32_e32 v224, v41
	v_sub_f32_e32 v41, v46, v209
	v_add_f32_e32 v40, v221, v40
	v_exp_f32_e32 v225, v41
	v_sub_f32_e32 v41, v47, v209
	v_add_f32_e32 v40, v222, v40
	v_exp_f32_e32 v226, v41
	v_add_f32_e32 v40, v223, v40
	v_add_f32_e32 v40, v224, v40
	v_add_f32_e32 v40, v225, v40
	v_exp_f32_e32 v120, v120
	v_add_f32_e32 v227, v226, v40
	ds_read_b64_tr_b16 v[40:41], v175 offset:4608
	ds_read_b64_tr_b16 v[42:43], v175 offset:5760
	v_cvt_pk_bf16_f32 v44, v210, v212
	v_cvt_pk_bf16_f32 v45, v213, v214
	v_cvt_pk_bf16_f32 v46, v215, v216
	v_cvt_pk_bf16_f32 v47, v217, v218
	ds_read_b64_tr_b16 v[212:213], v175 offset:6912
	ds_read_b64_tr_b16 v[214:215], v175 offset:8064
	ds_read_b64_tr_b16 v[218:219], v175 offset:5824
	ds_read_b64_tr_b16 v[216:217], v175 offset:4672
	v_pk_mul_f32 v[14:15], v[14:15], v[120:121] op_sel_hi:[1,0]
	v_pk_mul_f32 v[12:13], v[12:13], v[120:121] op_sel_hi:[1,0]
	v_pk_mul_f32 v[10:11], v[10:11], v[120:121] op_sel_hi:[1,0]
	v_pk_mul_f32 v[8:9], v[8:9], v[120:121] op_sel_hi:[1,0]
	v_pk_mul_f32 v[6:7], v[6:7], v[120:121] op_sel_hi:[1,0]
	v_pk_mul_f32 v[4:5], v[4:5], v[120:121] op_sel_hi:[1,0]
	v_pk_mul_f32 v[2:3], v[2:3], v[120:121] op_sel_hi:[1,0]
	v_pk_mul_f32 v[0:1], v[0:1], v[120:121] op_sel_hi:[1,0]
	v_pk_mul_f32 v[30:31], v[30:31], v[120:121] op_sel_hi:[1,0]
	v_pk_mul_f32 v[28:29], v[28:29], v[120:121] op_sel_hi:[1,0]
	v_pk_mul_f32 v[26:27], v[26:27], v[120:121] op_sel_hi:[1,0]
	v_pk_mul_f32 v[24:25], v[24:25], v[120:121] op_sel_hi:[1,0]
	v_pk_mul_f32 v[22:23], v[22:23], v[120:121] op_sel_hi:[1,0]
	v_pk_mul_f32 v[20:21], v[20:21], v[120:121] op_sel_hi:[1,0]
	v_pk_mul_f32 v[18:19], v[18:19], v[120:121] op_sel_hi:[1,0]
	v_pk_mul_f32 v[16:17], v[16:17], v[120:121] op_sel_hi:[1,0]
	s_waitcnt lgkmcnt(4)
	v_mfma_f32_32x32x16_bf16 v[0:15], v[40:43], v[44:47], v[0:15]
	v_cvt_pk_bf16_f32 v40, v220, v208
	v_cvt_pk_bf16_f32 v41, v221, v222
	v_cvt_pk_bf16_f32 v42, v223, v224
	ds_read_b64_tr_b16 v[222:223], v175 offset:8128
	ds_read_b64_tr_b16 v[220:221], v175 offset:6976
	v_cvt_pk_bf16_f32 v43, v225, v226
	s_waitcnt lgkmcnt(2)
	v_mfma_f32_32x32x16_bf16 v[16:31], v[216:219], v[44:47], v[16:31]
	ds_bpermute_b32 v44, v143, v227
	s_waitcnt lgkmcnt(0)
	v_add_f32_e32 v210, v227, v44
	v_fmac_f32_e32 v210, v202, v120
	v_mfma_f32_32x32x16_bf16 v[0:15], v[212:215], v[40:43], v[0:15]
	v_mfma_f32_32x32x16_bf16 v[16:31], v[220:223], v[40:43], v[16:31]
	s_cbranch_scc0 .LBB0_1328
	v_mov_b32_e32 v208, v209
	v_mov_b32_e32 v202, v210
	s_branch .LBB0_1284
